# weight-conversion items: all 32 W/scale loads issued before one wait (was a vmcnt(0) after every load); plus GLA chunk-scan load batching and RSCAN LDS swizzle
# speedup vs baseline: 1.1115x; 1.0805x over previous
; template <bool IS_ML>
; __device__ __forceinline__ void chunk_scan(unsigned char* ws, int gtid, int ngt) {
;     ...
;     for (int c0 = 0; c0 < 256; c0 += CB) {
;       float bv[CB], x0[CB], x1[CB], x2[CB];
; #pragma unroll
;       for (int j = 0; j < CB; ++j) { const int c = c0 + j;
;         bv[j] = bf2f(BS[((size_t)(c * 4 + h) * 256 + v) * 128 + d]);
;         if (IS_ML) { x0[j] = BL[c * 4 + h]; x1[j] = MLc[c * 4 + h]; x2[j] = (v == 0) ? DT[(c * 4 + h) * 128 + d] : 0.f; }
;         else { x0[j] = DT[(c * 4 + h) * 128 + d]; x1[j] = 0.f; x2[j] = 0.f; } }
.LBB0_323:
	s_waitcnt vmcnt(3)
	v_lshl_add_u64 v[40:41], s[84:85], 0, v[4:5]
	v_add_co_u32_e32 v36, vcc, s64, v40
	s_mov_b32 s7, 0x9e40000
	s_nop 0
	v_addc_co_u32_e32 v37, vcc, 0, v41, vcc
	global_load_ushort v130, v[36:37], off
	v_lshl_add_u64 v[88:89], s[84:85], 0, v[2:3]
	s_add_i32 s6, s6, 16
	v_lshl_add_u64 v[2:3], v[2:3], 0, s[78:79]
	v_lshl_add_u64 v[4:5], v[4:5], 0, s[80:81]
	s_cmpk_lt_u32 s6, 0xf0
	v_lshl_add_u64 v[38:39], s[84:85], 0, v[34:35]
	global_load_dword v90, v[38:39], off
	v_add_co_u32_e32 v38, vcc, s7, v40
	s_mov_b32 s7, 0x9e80000
	s_nop 0
	v_addc_co_u32_e32 v39, vcc, 0, v41, vcc
	global_load_ushort v131, v[38:39], off
	v_lshl_add_u64 v[34:35], v[34:35], 0, s[78:79]
	v_lshl_add_u64 v[42:43], s[84:85], 0, v[32:33]
	global_load_dword v92, v[42:43], off
	v_add_co_u32_e32 v42, vcc, s7, v40
	s_mov_b32 s7, 0x9ec0000
	s_nop 0
	v_addc_co_u32_e32 v43, vcc, 0, v41, vcc
	global_load_ushort v132, v[42:43], off
	v_lshl_add_u64 v[32:33], v[32:33], 0, s[78:79]
	v_lshl_add_u64 v[44:45], s[84:85], 0, v[30:31]
	global_load_dword v94, v[44:45], off
	v_add_co_u32_e32 v44, vcc, s7, v40
	s_mov_b32 s7, 0x9f00000
	s_nop 0
	v_addc_co_u32_e32 v45, vcc, 0, v41, vcc
	global_load_ushort v133, v[44:45], off
	v_lshl_add_u64 v[30:31], v[30:31], 0, s[78:79]
	v_lshl_add_u64 v[46:47], s[84:85], 0, v[28:29]
	global_load_dword v96, v[46:47], off
	v_add_co_u32_e32 v46, vcc, s7, v40
	s_mov_b32 s7, 0x9f40000
	s_nop 0
	v_addc_co_u32_e32 v47, vcc, 0, v41, vcc
	global_load_ushort v134, v[46:47], off
	v_lshl_add_u64 v[28:29], v[28:29], 0, s[78:79]
	v_lshl_add_u64 v[48:49], s[84:85], 0, v[26:27]
	global_load_dword v98, v[48:49], off
	v_add_co_u32_e32 v48, vcc, s7, v40
	s_mov_b32 s7, 0x9f80000
	s_nop 0
	v_addc_co_u32_e32 v49, vcc, 0, v41, vcc
	global_load_ushort v135, v[48:49], off
	v_lshl_add_u64 v[26:27], v[26:27], 0, s[78:79]
	v_lshl_add_u64 v[50:51], s[84:85], 0, v[24:25]
	global_load_dword v100, v[50:51], off
	v_add_co_u32_e32 v50, vcc, s7, v40
	s_mov_b32 s7, 0x9fc0000
	s_nop 0
	v_addc_co_u32_e32 v51, vcc, 0, v41, vcc
	global_load_ushort v136, v[50:51], off
	v_lshl_add_u64 v[24:25], v[24:25], 0, s[78:79]
	v_lshl_add_u64 v[52:53], s[84:85], 0, v[22:23]
	global_load_dword v102, v[52:53], off
	v_add_co_u32_e32 v52, vcc, s7, v40
	s_mov_b32 s7, 0xa000000
	s_nop 0
	v_addc_co_u32_e32 v53, vcc, 0, v41, vcc
	global_load_ushort v137, v[52:53], off
	v_lshl_add_u64 v[22:23], v[22:23], 0, s[78:79]
	v_lshl_add_u64 v[54:55], s[84:85], 0, v[20:21]
	global_load_dword v104, v[54:55], off
	v_add_co_u32_e32 v54, vcc, s7, v40
	s_mov_b32 s7, 0xa040000
	s_nop 0
	v_addc_co_u32_e32 v55, vcc, 0, v41, vcc
	global_load_ushort v138, v[54:55], off
	v_lshl_add_u64 v[20:21], v[20:21], 0, s[78:79]
	v_lshl_add_u64 v[56:57], s[84:85], 0, v[18:19]
	global_load_dword v106, v[56:57], off
	v_add_co_u32_e32 v56, vcc, s7, v40
	s_mov_b32 s7, 0xa080000
	s_nop 0
	v_addc_co_u32_e32 v57, vcc, 0, v41, vcc
	global_load_ushort v139, v[56:57], off
	v_lshl_add_u64 v[18:19], v[18:19], 0, s[78:79]
	v_lshl_add_u64 v[76:77], s[84:85], 0, v[16:17]
	global_load_dword v109, v[76:77], off
	v_add_co_u32_e32 v76, vcc, s7, v40
	s_mov_b32 s7, 0xa0c0000
	s_nop 0
	v_addc_co_u32_e32 v77, vcc, 0, v41, vcc
	global_load_ushort v140, v[76:77], off
	v_lshl_add_u64 v[16:17], v[16:17], 0, s[78:79]
	v_lshl_add_u64 v[78:79], s[84:85], 0, v[14:15]
	global_load_dword v111, v[78:79], off
	v_add_co_u32_e32 v78, vcc, s7, v40
	s_mov_b32 s7, 0xa100000
	s_nop 0
	v_addc_co_u32_e32 v79, vcc, 0, v41, vcc
	global_load_ushort v141, v[78:79], off
	v_lshl_add_u64 v[14:15], v[14:15], 0, s[78:79]
	v_lshl_add_u64 v[80:81], s[84:85], 0, v[12:13]
	global_load_dword v113, v[80:81], off
	v_add_co_u32_e32 v80, vcc, s7, v40
	s_mov_b32 s7, 0xa140000
	s_nop 0
	v_addc_co_u32_e32 v81, vcc, 0, v41, vcc
	global_load_ushort v142, v[80:81], off
	v_lshl_add_u64 v[12:13], v[12:13], 0, s[78:79]
	v_lshl_add_u64 v[82:83], s[84:85], 0, v[10:11]
	global_load_dword v115, v[82:83], off
	v_add_co_u32_e32 v82, vcc, s7, v40
	s_mov_b32 s7, 0xa180000
	s_nop 0
	v_addc_co_u32_e32 v83, vcc, 0, v41, vcc
	global_load_ushort v143, v[82:83], off
	v_lshl_add_u64 v[10:11], v[10:11], 0, s[78:79]
	v_lshl_add_u64 v[84:85], s[84:85], 0, v[8:9]
	global_load_dword v117, v[84:85], off
	v_add_co_u32_e32 v84, vcc, s7, v40
	s_mov_b32 s7, 0xa1c0000
	s_nop 0
	v_addc_co_u32_e32 v85, vcc, 0, v41, vcc
	global_load_ushort v144, v[84:85], off
	v_lshl_add_u64 v[8:9], v[8:9], 0, s[78:79]
	v_lshl_add_u64 v[86:87], s[84:85], 0, v[6:7]
	global_load_dword v119, v[86:87], off
	v_add_co_u32_e32 v86, vcc, s7, v40
	v_lshl_add_u64 v[6:7], v[6:7], 0, s[78:79]
	s_nop 0
	v_addc_co_u32_e32 v87, vcc, 0, v41, vcc
	global_load_ushort v145, v[86:87], off
	global_load_dword v41, v[88:89], off
	s_waitcnt vmcnt(0)
; __device__ __forceinline__ unsigned f2bf(float f) { unsigned u = __builtin_bit_cast(unsigned, f); return (u + 0x7fffu + ((u >> 16) & 1u)) >> 16; }
; template <bool IS_ML>
; __device__ __forceinline__ void chunk_scan(unsigned char* ws, int gtid, int ngt) {
;     ...
; #pragma unroll
;       for (int j = 0; j < CB; ++j) { const int c = c0 + j;
;         BS[((size_t)(c * 4 + h) * 256 + v) * 128 + d] = (bf16_t)f2bf(st);
;         if (IS_ML) {
;           const float bl = x0[j], ml = x1[j]; const float mn = fmaxf(bl + m, ml);
;           const float cs = __expf(bl + m - mn), wsc = __expf(ml - mn);
;           st = cs * st + wsc * bv[j];
;           if (v == 0) { NST[(c * 4 + h) * 128 + d] = n; n = cs * n + wsc * x2[j]; if (d == 0) MST[c * 4 + h] = m; }
;           m = mn;
;         } else st = st * __expf(x0[j]) + bv[j];
;       }
	v_lshlrev_b32_e32 v75, 16, v130
	v_lshlrev_b32_e32 v91, 16, v131
	v_lshlrev_b32_e32 v93, 16, v132
	v_lshlrev_b32_e32 v95, 16, v133
	v_lshlrev_b32_e32 v97, 16, v134
	v_lshlrev_b32_e32 v99, 16, v135
	v_lshlrev_b32_e32 v101, 16, v136
	v_lshlrev_b32_e32 v103, 16, v137
	v_lshlrev_b32_e32 v105, 16, v138
	v_lshlrev_b32_e32 v107, 16, v139
	v_lshlrev_b32_e32 v110, 16, v140
	v_lshlrev_b32_e32 v112, 16, v141
	v_lshlrev_b32_e32 v114, 16, v142
	v_lshlrev_b32_e32 v116, 16, v143
	v_lshlrev_b32_e32 v118, 16, v144
	v_lshlrev_b32_e32 v40, 16, v145
	v_bfe_u32 v88, v74, 16, 1
	v_add3_u32 v88, v74, v88, s65
	global_store_short_d16_hi v[36:37], v88, off
	v_mul_f32_e32 v36, 0x3fb8aa3b, v90
	v_exp_f32_e32 v36, v36
	s_waitcnt vmcnt(2)
	v_fmac_f32_e32 v75, v74, v36
	v_bfe_u32 v36, v75, 16, 1
	v_add3_u32 v36, v75, v36, s65
	global_store_short_d16_hi v[38:39], v36, off
	v_mul_f32_e32 v36, 0x3fb8aa3b, v92
	v_exp_f32_e32 v36, v36
	s_nop 0
	v_fmac_f32_e32 v91, v75, v36
	v_bfe_u32 v36, v91, 16, 1
	v_add3_u32 v36, v91, v36, s65
	global_store_short_d16_hi v[42:43], v36, off
	v_mul_f32_e32 v36, 0x3fb8aa3b, v94
	v_exp_f32_e32 v36, v36
	s_nop 0
	v_fmac_f32_e32 v93, v91, v36
	v_bfe_u32 v36, v93, 16, 1
	v_add3_u32 v36, v93, v36, s65
	global_store_short_d16_hi v[44:45], v36, off
	v_mul_f32_e32 v36, 0x3fb8aa3b, v96
	v_exp_f32_e32 v36, v36
	s_nop 0
	v_fmac_f32_e32 v95, v93, v36
	v_bfe_u32 v36, v95, 16, 1
	v_add3_u32 v36, v95, v36, s65
	global_store_short_d16_hi v[46:47], v36, off
	v_mul_f32_e32 v36, 0x3fb8aa3b, v98
	v_exp_f32_e32 v36, v36
	s_nop 0
	v_fmac_f32_e32 v97, v95, v36
	v_bfe_u32 v36, v97, 16, 1
	v_add3_u32 v36, v97, v36, s65
	global_store_short_d16_hi v[48:49], v36, off
	v_mul_f32_e32 v36, 0x3fb8aa3b, v100
	v_exp_f32_e32 v36, v36
	s_nop 0
	v_fmac_f32_e32 v99, v97, v36
	v_bfe_u32 v36, v99, 16, 1
	v_add3_u32 v36, v99, v36, s65
	global_store_short_d16_hi v[50:51], v36, off
	v_mul_f32_e32 v36, 0x3fb8aa3b, v102
	v_exp_f32_e32 v36, v36
	s_nop 0
	v_fmac_f32_e32 v101, v99, v36
	v_bfe_u32 v36, v101, 16, 1
	v_add3_u32 v36, v101, v36, s65
	global_store_short_d16_hi v[52:53], v36, off
	v_mul_f32_e32 v36, 0x3fb8aa3b, v104
	v_exp_f32_e32 v36, v36
	s_nop 0
	v_fmac_f32_e32 v103, v101, v36
	v_bfe_u32 v36, v103, 16, 1
	v_add3_u32 v36, v103, v36, s65
	global_store_short_d16_hi v[54:55], v36, off
	v_mul_f32_e32 v36, 0x3fb8aa3b, v106
	v_exp_f32_e32 v36, v36
	s_nop 0
	v_fmac_f32_e32 v105, v103, v36
	v_bfe_u32 v36, v105, 16, 1
	v_add3_u32 v36, v105, v36, s65
	global_store_short_d16_hi v[56:57], v36, off
	v_mul_f32_e32 v36, 0x3fb8aa3b, v109
	v_exp_f32_e32 v36, v36
	s_nop 0
	v_fmac_f32_e32 v107, v105, v36
	v_bfe_u32 v36, v107, 16, 1
	v_add3_u32 v36, v107, v36, s65
	global_store_short_d16_hi v[76:77], v36, off
	v_mul_f32_e32 v36, 0x3fb8aa3b, v111
	v_exp_f32_e32 v36, v36
	s_nop 0
	v_fmac_f32_e32 v110, v107, v36
	v_bfe_u32 v36, v110, 16, 1
	v_add3_u32 v36, v110, v36, s65
	global_store_short_d16_hi v[78:79], v36, off
	v_mul_f32_e32 v36, 0x3fb8aa3b, v113
	v_exp_f32_e32 v36, v36
	s_nop 0
	v_fmac_f32_e32 v112, v110, v36
	v_bfe_u32 v36, v112, 16, 1
	v_add3_u32 v36, v112, v36, s65
	global_store_short_d16_hi v[80:81], v36, off
	v_mul_f32_e32 v36, 0x3fb8aa3b, v115
	v_exp_f32_e32 v36, v36
	s_nop 0
	v_fmac_f32_e32 v114, v112, v36
	v_bfe_u32 v36, v114, 16, 1
	v_add3_u32 v36, v114, v36, s65
	global_store_short_d16_hi v[82:83], v36, off
	v_mul_f32_e32 v36, 0x3fb8aa3b, v117
	v_exp_f32_e32 v36, v36
	s_nop 0
	v_fmac_f32_e32 v116, v114, v36
	v_bfe_u32 v36, v116, 16, 1
	v_add3_u32 v36, v116, v36, s65
	global_store_short_d16_hi v[84:85], v36, off
	v_mul_f32_e32 v36, 0x3fb8aa3b, v119
	v_exp_f32_e32 v36, v36
	s_nop 0
	v_fmac_f32_e32 v118, v116, v36
	v_bfe_u32 v36, v118, 16, 1
	v_add3_u32 v36, v118, v36, s65
	global_store_short_d16_hi v[86:87], v36, off
	s_waitcnt vmcnt(16)
	v_mul_f32_e32 v36, 0x3fb8aa3b, v41
	v_exp_f32_e32 v36, v36
	s_nop 0
	v_fmac_f32_e32 v40, v118, v36
	v_mov_b32_e32 v74, v40
	s_cbranch_scc1 .LBB0_323
	v_add_u32_e32 v108, s14, v108
	s_mov_b32 s6, 0x1ffff
	v_cmp_lt_i32_e32 vcc, s6, v108
	s_or_b64 s[4:5], vcc, s[4:5]
	s_andn2_b64 exec, exec, s[4:5]
	s_cbranch_execnz .LBB0_322

; __device__ __forceinline__ void conv_item(const ConvJob& J, const float* W, const float* sc, bf16_t* out, LAS float* scr, int item, int lane) {
;     ...
;   for (int i = 0; i < 32; ++i) { const int cc = 2 * i + (lane >> 5); const int k = c0 + cc - J.k_off; const int n = n0 + (lane & 31);
;     float v = 0.f;
;     if (k >= 0 && k < J.K && n < J.N) { v = W[(size_t)k * J.N + n]; if (J.sc_mode == 1) v *= sc[k]; else if (J.sc_mode == 2) v *= (1.f - sc[k]); }
;     scr[cc * 33 + (lane & 31)] = v; }
.LBB0_926:
	v_add_u32_e32 v32, s36, v3
	v_mov_b32_e32 v31, 0
	v_mov_b32_e32 v30, v32
	v_cmp_gt_i32_e32 vcc, 0, v30
	v_cmp_le_i32_e64 s[4:5], s6, v30
	v_mov_b32_e32 v40, 0
	v_mov_b32_e32 v72, 0
	s_or_b64 s[4:5], vcc, s[4:5]
	s_nor_b64 s[14:15], s[4:5], s[0:1]
	s_and_saveexec_b64 s[4:5], s[14:15]
	v_mad_u64_u32 v[34:35], vcc, v30, s28, 0
	v_lshl_add_u64 v[34:35], v[34:35], 2, v[8:9]
	global_load_dword v40, v[34:35], off
	s_cmp_eq_u32 s27, 0
	s_cbranch_scc1 .Lcv_ns_0
	v_lshl_add_u64 v[36:37], v[30:31], 2, v[6:7]
	global_load_dword v72, v[36:37], off
.Lcv_ns_0:
	s_or_b64 exec, exec, s[4:5]
	v_add_u32_e32 v30, 2, v32
	v_cmp_gt_i32_e32 vcc, 0, v30
	v_cmp_le_i32_e64 s[4:5], s6, v30
	v_mov_b32_e32 v41, 0
	v_mov_b32_e32 v73, 0
	s_or_b64 s[4:5], vcc, s[4:5]
	s_nor_b64 s[14:15], s[4:5], s[0:1]
	s_and_saveexec_b64 s[4:5], s[14:15]
	v_mad_u64_u32 v[34:35], vcc, v30, s28, 0
	v_lshl_add_u64 v[34:35], v[34:35], 2, v[8:9]
	global_load_dword v41, v[34:35], off
	s_cmp_eq_u32 s27, 0
	s_cbranch_scc1 .Lcv_ns_1
	v_lshl_add_u64 v[36:37], v[30:31], 2, v[6:7]
	global_load_dword v73, v[36:37], off
.Lcv_ns_1:
	s_or_b64 exec, exec, s[4:5]
	v_add_u32_e32 v30, 4, v32
	v_cmp_gt_i32_e32 vcc, 0, v30
	v_cmp_le_i32_e64 s[4:5], s6, v30
	v_mov_b32_e32 v42, 0
	v_mov_b32_e32 v74, 0
	s_or_b64 s[4:5], vcc, s[4:5]
	s_nor_b64 s[14:15], s[4:5], s[0:1]
	s_and_saveexec_b64 s[4:5], s[14:15]
	v_mad_u64_u32 v[34:35], vcc, v30, s28, 0
	v_lshl_add_u64 v[34:35], v[34:35], 2, v[8:9]
	global_load_dword v42, v[34:35], off
	s_cmp_eq_u32 s27, 0
	s_cbranch_scc1 .Lcv_ns_2
	v_lshl_add_u64 v[36:37], v[30:31], 2, v[6:7]
	global_load_dword v74, v[36:37], off
.Lcv_ns_2:
	s_or_b64 exec, exec, s[4:5]
	v_add_u32_e32 v30, 6, v32
	v_cmp_gt_i32_e32 vcc, 0, v30
	v_cmp_le_i32_e64 s[4:5], s6, v30
	v_mov_b32_e32 v43, 0
	v_mov_b32_e32 v75, 0
	s_or_b64 s[4:5], vcc, s[4:5]
	s_nor_b64 s[14:15], s[4:5], s[0:1]
	s_and_saveexec_b64 s[4:5], s[14:15]
	v_mad_u64_u32 v[34:35], vcc, v30, s28, 0
	v_lshl_add_u64 v[34:35], v[34:35], 2, v[8:9]
	global_load_dword v43, v[34:35], off
	s_cmp_eq_u32 s27, 0
	s_cbranch_scc1 .Lcv_ns_3
	v_lshl_add_u64 v[36:37], v[30:31], 2, v[6:7]
	global_load_dword v75, v[36:37], off
.Lcv_ns_3:
	s_or_b64 exec, exec, s[4:5]
	v_add_u32_e32 v30, 8, v32
	v_cmp_gt_i32_e32 vcc, 0, v30
	v_cmp_le_i32_e64 s[4:5], s6, v30
	v_mov_b32_e32 v44, 0
	v_mov_b32_e32 v76, 0
	s_or_b64 s[4:5], vcc, s[4:5]
	s_nor_b64 s[14:15], s[4:5], s[0:1]
	s_and_saveexec_b64 s[4:5], s[14:15]
	v_mad_u64_u32 v[34:35], vcc, v30, s28, 0
	v_lshl_add_u64 v[34:35], v[34:35], 2, v[8:9]
	global_load_dword v44, v[34:35], off
	s_cmp_eq_u32 s27, 0
	s_cbranch_scc1 .Lcv_ns_4
	v_lshl_add_u64 v[36:37], v[30:31], 2, v[6:7]
	global_load_dword v76, v[36:37], off
.Lcv_ns_4:
	s_or_b64 exec, exec, s[4:5]
	v_add_u32_e32 v30, 10, v32
	v_cmp_gt_i32_e32 vcc, 0, v30
	v_cmp_le_i32_e64 s[4:5], s6, v30
	v_mov_b32_e32 v45, 0
	v_mov_b32_e32 v77, 0
	s_or_b64 s[4:5], vcc, s[4:5]
	s_nor_b64 s[14:15], s[4:5], s[0:1]
	s_and_saveexec_b64 s[4:5], s[14:15]
	v_mad_u64_u32 v[34:35], vcc, v30, s28, 0
	v_lshl_add_u64 v[34:35], v[34:35], 2, v[8:9]
	global_load_dword v45, v[34:35], off
	s_cmp_eq_u32 s27, 0
	s_cbranch_scc1 .Lcv_ns_5
	v_lshl_add_u64 v[36:37], v[30:31], 2, v[6:7]
	global_load_dword v77, v[36:37], off
.Lcv_ns_5:
	s_or_b64 exec, exec, s[4:5]
	v_add_u32_e32 v30, 12, v32
	v_cmp_gt_i32_e32 vcc, 0, v30
	v_cmp_le_i32_e64 s[4:5], s6, v30
	v_mov_b32_e32 v46, 0
	v_mov_b32_e32 v78, 0
	s_or_b64 s[4:5], vcc, s[4:5]
	s_nor_b64 s[14:15], s[4:5], s[0:1]
	s_and_saveexec_b64 s[4:5], s[14:15]
	v_mad_u64_u32 v[34:35], vcc, v30, s28, 0
	v_lshl_add_u64 v[34:35], v[34:35], 2, v[8:9]
	global_load_dword v46, v[34:35], off
	s_cmp_eq_u32 s27, 0
	s_cbranch_scc1 .Lcv_ns_6
	v_lshl_add_u64 v[36:37], v[30:31], 2, v[6:7]
	global_load_dword v78, v[36:37], off
.Lcv_ns_6:
	s_or_b64 exec, exec, s[4:5]
	v_add_u32_e32 v30, 14, v32
	v_cmp_gt_i32_e32 vcc, 0, v30
	v_cmp_le_i32_e64 s[4:5], s6, v30
	v_mov_b32_e32 v47, 0
	v_mov_b32_e32 v79, 0
	s_or_b64 s[4:5], vcc, s[4:5]
	s_nor_b64 s[14:15], s[4:5], s[0:1]
	s_and_saveexec_b64 s[4:5], s[14:15]
	v_mad_u64_u32 v[34:35], vcc, v30, s28, 0
	v_lshl_add_u64 v[34:35], v[34:35], 2, v[8:9]
	global_load_dword v47, v[34:35], off
	s_cmp_eq_u32 s27, 0
	s_cbranch_scc1 .Lcv_ns_7
	v_lshl_add_u64 v[36:37], v[30:31], 2, v[6:7]
	global_load_dword v79, v[36:37], off
.Lcv_ns_7:
	s_or_b64 exec, exec, s[4:5]
	v_add_u32_e32 v30, 16, v32
	v_cmp_gt_i32_e32 vcc, 0, v30
	v_cmp_le_i32_e64 s[4:5], s6, v30
	v_mov_b32_e32 v48, 0
	v_mov_b32_e32 v80, 0
	s_or_b64 s[4:5], vcc, s[4:5]
	s_nor_b64 s[14:15], s[4:5], s[0:1]
	s_and_saveexec_b64 s[4:5], s[14:15]
	v_mad_u64_u32 v[34:35], vcc, v30, s28, 0
	v_lshl_add_u64 v[34:35], v[34:35], 2, v[8:9]
	global_load_dword v48, v[34:35], off
	s_cmp_eq_u32 s27, 0
	s_cbranch_scc1 .Lcv_ns_8
	v_lshl_add_u64 v[36:37], v[30:31], 2, v[6:7]
	global_load_dword v80, v[36:37], off
.Lcv_ns_8:
	s_or_b64 exec, exec, s[4:5]
	v_add_u32_e32 v30, 18, v32
	v_cmp_gt_i32_e32 vcc, 0, v30
	v_cmp_le_i32_e64 s[4:5], s6, v30
	v_mov_b32_e32 v49, 0
	v_mov_b32_e32 v81, 0
	s_or_b64 s[4:5], vcc, s[4:5]
	s_nor_b64 s[14:15], s[4:5], s[0:1]
	s_and_saveexec_b64 s[4:5], s[14:15]
	v_mad_u64_u32 v[34:35], vcc, v30, s28, 0
	v_lshl_add_u64 v[34:35], v[34:35], 2, v[8:9]
	global_load_dword v49, v[34:35], off
	s_cmp_eq_u32 s27, 0
	s_cbranch_scc1 .Lcv_ns_9
	v_lshl_add_u64 v[36:37], v[30:31], 2, v[6:7]
	global_load_dword v81, v[36:37], off
; __device__ __forceinline__ void conv_item(const ConvJob& J, const float* W, const float* sc, bf16_t* out, LAS float* scr, int item, int lane) {
;     ...
;   for (int i = 0; i < 32; ++i) { const int cc = 2 * i + (lane >> 5); const int k = c0 + cc - J.k_off; const int n = n0 + (lane & 31);
;     float v = 0.f;
;     if (k >= 0 && k < J.K && n < J.N) { v = W[(size_t)k * J.N + n]; if (J.sc_mode == 1) v *= sc[k]; else if (J.sc_mode == 2) v *= (1.f - sc[k]); }
.Lcv_ns_9:
	s_or_b64 exec, exec, s[4:5]
	v_add_u32_e32 v30, 20, v32
	v_cmp_gt_i32_e32 vcc, 0, v30
	v_cmp_le_i32_e64 s[4:5], s6, v30
	v_mov_b32_e32 v50, 0
	v_mov_b32_e32 v82, 0
	s_or_b64 s[4:5], vcc, s[4:5]
	s_nor_b64 s[14:15], s[4:5], s[0:1]
	s_and_saveexec_b64 s[4:5], s[14:15]
	v_mad_u64_u32 v[34:35], vcc, v30, s28, 0
	v_lshl_add_u64 v[34:35], v[34:35], 2, v[8:9]
	global_load_dword v50, v[34:35], off
	s_cmp_eq_u32 s27, 0
	s_cbranch_scc1 .Lcv_ns_10
	v_lshl_add_u64 v[36:37], v[30:31], 2, v[6:7]
	global_load_dword v82, v[36:37], off
.Lcv_ns_10:
	s_or_b64 exec, exec, s[4:5]
	v_add_u32_e32 v30, 22, v32
	v_cmp_gt_i32_e32 vcc, 0, v30
	v_cmp_le_i32_e64 s[4:5], s6, v30
	v_mov_b32_e32 v51, 0
	v_mov_b32_e32 v83, 0
	s_or_b64 s[4:5], vcc, s[4:5]
	s_nor_b64 s[14:15], s[4:5], s[0:1]
	s_and_saveexec_b64 s[4:5], s[14:15]
	v_mad_u64_u32 v[34:35], vcc, v30, s28, 0
	v_lshl_add_u64 v[34:35], v[34:35], 2, v[8:9]
	global_load_dword v51, v[34:35], off
	s_cmp_eq_u32 s27, 0
	s_cbranch_scc1 .Lcv_ns_11
	v_lshl_add_u64 v[36:37], v[30:31], 2, v[6:7]
	global_load_dword v83, v[36:37], off
.Lcv_ns_11:
	s_or_b64 exec, exec, s[4:5]
	v_add_u32_e32 v30, 24, v32
	v_cmp_gt_i32_e32 vcc, 0, v30
	v_cmp_le_i32_e64 s[4:5], s6, v30
	v_mov_b32_e32 v52, 0
	v_mov_b32_e32 v84, 0
	s_or_b64 s[4:5], vcc, s[4:5]
	s_nor_b64 s[14:15], s[4:5], s[0:1]
	s_and_saveexec_b64 s[4:5], s[14:15]
	v_mad_u64_u32 v[34:35], vcc, v30, s28, 0
	v_lshl_add_u64 v[34:35], v[34:35], 2, v[8:9]
	global_load_dword v52, v[34:35], off
	s_cmp_eq_u32 s27, 0
	s_cbranch_scc1 .Lcv_ns_12
	v_lshl_add_u64 v[36:37], v[30:31], 2, v[6:7]
	global_load_dword v84, v[36:37], off
.Lcv_ns_12:
	s_or_b64 exec, exec, s[4:5]
	v_add_u32_e32 v30, 26, v32
	v_cmp_gt_i32_e32 vcc, 0, v30
	v_cmp_le_i32_e64 s[4:5], s6, v30
	v_mov_b32_e32 v53, 0
	v_mov_b32_e32 v85, 0
	s_or_b64 s[4:5], vcc, s[4:5]
	s_nor_b64 s[14:15], s[4:5], s[0:1]
	s_and_saveexec_b64 s[4:5], s[14:15]
	v_mad_u64_u32 v[34:35], vcc, v30, s28, 0
	v_lshl_add_u64 v[34:35], v[34:35], 2, v[8:9]
	global_load_dword v53, v[34:35], off
	s_cmp_eq_u32 s27, 0
	s_cbranch_scc1 .Lcv_ns_13
	v_lshl_add_u64 v[36:37], v[30:31], 2, v[6:7]
	global_load_dword v85, v[36:37], off
.Lcv_ns_13:
	s_or_b64 exec, exec, s[4:5]
	v_add_u32_e32 v30, 28, v32
	v_cmp_gt_i32_e32 vcc, 0, v30
	v_cmp_le_i32_e64 s[4:5], s6, v30
	v_mov_b32_e32 v54, 0
	v_mov_b32_e32 v86, 0
	s_or_b64 s[4:5], vcc, s[4:5]
	s_nor_b64 s[14:15], s[4:5], s[0:1]
	s_and_saveexec_b64 s[4:5], s[14:15]
	v_mad_u64_u32 v[34:35], vcc, v30, s28, 0
	v_lshl_add_u64 v[34:35], v[34:35], 2, v[8:9]
	global_load_dword v54, v[34:35], off
	s_cmp_eq_u32 s27, 0
	s_cbranch_scc1 .Lcv_ns_14
	v_lshl_add_u64 v[36:37], v[30:31], 2, v[6:7]
	global_load_dword v86, v[36:37], off
.Lcv_ns_14:
	s_or_b64 exec, exec, s[4:5]
	v_add_u32_e32 v30, 30, v32
	v_cmp_gt_i32_e32 vcc, 0, v30
	v_cmp_le_i32_e64 s[4:5], s6, v30
	v_mov_b32_e32 v55, 0
	v_mov_b32_e32 v87, 0
	s_or_b64 s[4:5], vcc, s[4:5]
	s_nor_b64 s[14:15], s[4:5], s[0:1]
	s_and_saveexec_b64 s[4:5], s[14:15]
	v_mad_u64_u32 v[34:35], vcc, v30, s28, 0
	v_lshl_add_u64 v[34:35], v[34:35], 2, v[8:9]
	global_load_dword v55, v[34:35], off
	s_cmp_eq_u32 s27, 0
	s_cbranch_scc1 .Lcv_ns_15
	v_lshl_add_u64 v[36:37], v[30:31], 2, v[6:7]
	global_load_dword v87, v[36:37], off
.Lcv_ns_15:
	s_or_b64 exec, exec, s[4:5]
	v_add_u32_e32 v30, 32, v32
	v_cmp_gt_i32_e32 vcc, 0, v30
	v_cmp_le_i32_e64 s[4:5], s6, v30
	v_mov_b32_e32 v56, 0
	v_mov_b32_e32 v88, 0
	s_or_b64 s[4:5], vcc, s[4:5]
	s_nor_b64 s[14:15], s[4:5], s[0:1]
	s_and_saveexec_b64 s[4:5], s[14:15]
	v_mad_u64_u32 v[34:35], vcc, v30, s28, 0
	v_lshl_add_u64 v[34:35], v[34:35], 2, v[8:9]
	global_load_dword v56, v[34:35], off
	s_cmp_eq_u32 s27, 0
	s_cbranch_scc1 .Lcv_ns_16
	v_lshl_add_u64 v[36:37], v[30:31], 2, v[6:7]
	global_load_dword v88, v[36:37], off
.Lcv_ns_16:
	s_or_b64 exec, exec, s[4:5]
	v_add_u32_e32 v30, 34, v32
	v_cmp_gt_i32_e32 vcc, 0, v30
	v_cmp_le_i32_e64 s[4:5], s6, v30
	v_mov_b32_e32 v57, 0
	v_mov_b32_e32 v89, 0
	s_or_b64 s[4:5], vcc, s[4:5]
	s_nor_b64 s[14:15], s[4:5], s[0:1]
	s_and_saveexec_b64 s[4:5], s[14:15]
	v_mad_u64_u32 v[34:35], vcc, v30, s28, 0
	v_lshl_add_u64 v[34:35], v[34:35], 2, v[8:9]
	global_load_dword v57, v[34:35], off
	s_cmp_eq_u32 s27, 0
	s_cbranch_scc1 .Lcv_ns_17
	v_lshl_add_u64 v[36:37], v[30:31], 2, v[6:7]
	global_load_dword v89, v[36:37], off
.Lcv_ns_17:
	s_or_b64 exec, exec, s[4:5]
	v_add_u32_e32 v30, 36, v32
	v_cmp_gt_i32_e32 vcc, 0, v30
	v_cmp_le_i32_e64 s[4:5], s6, v30
	v_mov_b32_e32 v58, 0
	v_mov_b32_e32 v90, 0
	s_or_b64 s[4:5], vcc, s[4:5]
	s_nor_b64 s[14:15], s[4:5], s[0:1]
	s_and_saveexec_b64 s[4:5], s[14:15]
	v_mad_u64_u32 v[34:35], vcc, v30, s28, 0
	v_lshl_add_u64 v[34:35], v[34:35], 2, v[8:9]
	global_load_dword v58, v[34:35], off
	s_cmp_eq_u32 s27, 0
	s_cbranch_scc1 .Lcv_ns_18
	v_lshl_add_u64 v[36:37], v[30:31], 2, v[6:7]
	global_load_dword v90, v[36:37], off
.Lcv_ns_18:
	s_or_b64 exec, exec, s[4:5]
	v_add_u32_e32 v30, 38, v32
	v_cmp_gt_i32_e32 vcc, 0, v30
	v_cmp_le_i32_e64 s[4:5], s6, v30
	v_mov_b32_e32 v59, 0
	v_mov_b32_e32 v91, 0
	s_or_b64 s[4:5], vcc, s[4:5]
	s_nor_b64 s[14:15], s[4:5], s[0:1]
	s_and_saveexec_b64 s[4:5], s[14:15]
	v_mad_u64_u32 v[34:35], vcc, v30, s28, 0
	v_lshl_add_u64 v[34:35], v[34:35], 2, v[8:9]
	global_load_dword v59, v[34:35], off
	s_cmp_eq_u32 s27, 0
	s_cbranch_scc1 .Lcv_ns_19
	v_lshl_add_u64 v[36:37], v[30:31], 2, v[6:7]
	global_load_dword v91, v[36:37], off
; __device__ __forceinline__ void conv_item(const ConvJob& J, const float* W, const float* sc, bf16_t* out, LAS float* scr, int item, int lane) {
;     ...
;   for (int i = 0; i < 32; ++i) { const int cc = 2 * i + (lane >> 5); const int k = c0 + cc - J.k_off; const int n = n0 + (lane & 31);
;     float v = 0.f;
;     if (k >= 0 && k < J.K && n < J.N) { v = W[(size_t)k * J.N + n]; if (J.sc_mode == 1) v *= sc[k]; else if (J.sc_mode == 2) v *= (1.f - sc[k]); }
.Lcv_ns_19:
	s_or_b64 exec, exec, s[4:5]
	v_add_u32_e32 v30, 40, v32
	v_cmp_gt_i32_e32 vcc, 0, v30
	v_cmp_le_i32_e64 s[4:5], s6, v30
	v_mov_b32_e32 v60, 0
	v_mov_b32_e32 v92, 0
	s_or_b64 s[4:5], vcc, s[4:5]
	s_nor_b64 s[14:15], s[4:5], s[0:1]
	s_and_saveexec_b64 s[4:5], s[14:15]
	v_mad_u64_u32 v[34:35], vcc, v30, s28, 0
	v_lshl_add_u64 v[34:35], v[34:35], 2, v[8:9]
	global_load_dword v60, v[34:35], off
	s_cmp_eq_u32 s27, 0
	s_cbranch_scc1 .Lcv_ns_20
	v_lshl_add_u64 v[36:37], v[30:31], 2, v[6:7]
	global_load_dword v92, v[36:37], off
.Lcv_ns_20:
	s_or_b64 exec, exec, s[4:5]
	v_add_u32_e32 v30, 42, v32
	v_cmp_gt_i32_e32 vcc, 0, v30
	v_cmp_le_i32_e64 s[4:5], s6, v30
	v_mov_b32_e32 v61, 0
	v_mov_b32_e32 v93, 0
	s_or_b64 s[4:5], vcc, s[4:5]
	s_nor_b64 s[14:15], s[4:5], s[0:1]
	s_and_saveexec_b64 s[4:5], s[14:15]
	v_mad_u64_u32 v[34:35], vcc, v30, s28, 0
	v_lshl_add_u64 v[34:35], v[34:35], 2, v[8:9]
	global_load_dword v61, v[34:35], off
	s_cmp_eq_u32 s27, 0
	s_cbranch_scc1 .Lcv_ns_21
	v_lshl_add_u64 v[36:37], v[30:31], 2, v[6:7]
	global_load_dword v93, v[36:37], off
.Lcv_ns_21:
	s_or_b64 exec, exec, s[4:5]
	v_add_u32_e32 v30, 44, v32
	v_cmp_gt_i32_e32 vcc, 0, v30
	v_cmp_le_i32_e64 s[4:5], s6, v30
	v_mov_b32_e32 v62, 0
	v_mov_b32_e32 v94, 0
	s_or_b64 s[4:5], vcc, s[4:5]
	s_nor_b64 s[14:15], s[4:5], s[0:1]
	s_and_saveexec_b64 s[4:5], s[14:15]
	v_mad_u64_u32 v[34:35], vcc, v30, s28, 0
	v_lshl_add_u64 v[34:35], v[34:35], 2, v[8:9]
	global_load_dword v62, v[34:35], off
	s_cmp_eq_u32 s27, 0
	s_cbranch_scc1 .Lcv_ns_22
	v_lshl_add_u64 v[36:37], v[30:31], 2, v[6:7]
	global_load_dword v94, v[36:37], off
.Lcv_ns_22:
	s_or_b64 exec, exec, s[4:5]
	v_add_u32_e32 v30, 46, v32
	v_cmp_gt_i32_e32 vcc, 0, v30
	v_cmp_le_i32_e64 s[4:5], s6, v30
	v_mov_b32_e32 v63, 0
	v_mov_b32_e32 v95, 0
	s_or_b64 s[4:5], vcc, s[4:5]
	s_nor_b64 s[14:15], s[4:5], s[0:1]
	s_and_saveexec_b64 s[4:5], s[14:15]
	v_mad_u64_u32 v[34:35], vcc, v30, s28, 0
	v_lshl_add_u64 v[34:35], v[34:35], 2, v[8:9]
	global_load_dword v63, v[34:35], off
	s_cmp_eq_u32 s27, 0
	s_cbranch_scc1 .Lcv_ns_23
	v_lshl_add_u64 v[36:37], v[30:31], 2, v[6:7]
	global_load_dword v95, v[36:37], off
.Lcv_ns_23:
	s_or_b64 exec, exec, s[4:5]
	v_add_u32_e32 v30, 48, v32
	v_cmp_gt_i32_e32 vcc, 0, v30
	v_cmp_le_i32_e64 s[4:5], s6, v30
	v_mov_b32_e32 v64, 0
	v_mov_b32_e32 v96, 0
	s_or_b64 s[4:5], vcc, s[4:5]
	s_nor_b64 s[14:15], s[4:5], s[0:1]
	s_and_saveexec_b64 s[4:5], s[14:15]
	v_mad_u64_u32 v[34:35], vcc, v30, s28, 0
	v_lshl_add_u64 v[34:35], v[34:35], 2, v[8:9]
	global_load_dword v64, v[34:35], off
	s_cmp_eq_u32 s27, 0
	s_cbranch_scc1 .Lcv_ns_24
	v_lshl_add_u64 v[36:37], v[30:31], 2, v[6:7]
	global_load_dword v96, v[36:37], off
.Lcv_ns_24:
	s_or_b64 exec, exec, s[4:5]
	v_add_u32_e32 v30, 50, v32
	v_cmp_gt_i32_e32 vcc, 0, v30
	v_cmp_le_i32_e64 s[4:5], s6, v30
	v_mov_b32_e32 v65, 0
	v_mov_b32_e32 v97, 0
	s_or_b64 s[4:5], vcc, s[4:5]
	s_nor_b64 s[14:15], s[4:5], s[0:1]
	s_and_saveexec_b64 s[4:5], s[14:15]
	v_mad_u64_u32 v[34:35], vcc, v30, s28, 0
	v_lshl_add_u64 v[34:35], v[34:35], 2, v[8:9]
	global_load_dword v65, v[34:35], off
	s_cmp_eq_u32 s27, 0
	s_cbranch_scc1 .Lcv_ns_25
	v_lshl_add_u64 v[36:37], v[30:31], 2, v[6:7]
	global_load_dword v97, v[36:37], off
.Lcv_ns_25:
	s_or_b64 exec, exec, s[4:5]
	v_add_u32_e32 v30, 52, v32
	v_cmp_gt_i32_e32 vcc, 0, v30
	v_cmp_le_i32_e64 s[4:5], s6, v30
	v_mov_b32_e32 v66, 0
	v_mov_b32_e32 v98, 0
	s_or_b64 s[4:5], vcc, s[4:5]
	s_nor_b64 s[14:15], s[4:5], s[0:1]
	s_and_saveexec_b64 s[4:5], s[14:15]
	v_mad_u64_u32 v[34:35], vcc, v30, s28, 0
	v_lshl_add_u64 v[34:35], v[34:35], 2, v[8:9]
	global_load_dword v66, v[34:35], off
	s_cmp_eq_u32 s27, 0
	s_cbranch_scc1 .Lcv_ns_26
	v_lshl_add_u64 v[36:37], v[30:31], 2, v[6:7]
	global_load_dword v98, v[36:37], off
.Lcv_ns_26:
	s_or_b64 exec, exec, s[4:5]
	v_add_u32_e32 v30, 54, v32
	v_cmp_gt_i32_e32 vcc, 0, v30
	v_cmp_le_i32_e64 s[4:5], s6, v30
	v_mov_b32_e32 v67, 0
	v_mov_b32_e32 v99, 0
	s_or_b64 s[4:5], vcc, s[4:5]
	s_nor_b64 s[14:15], s[4:5], s[0:1]
	s_and_saveexec_b64 s[4:5], s[14:15]
	v_mad_u64_u32 v[34:35], vcc, v30, s28, 0
	v_lshl_add_u64 v[34:35], v[34:35], 2, v[8:9]
	global_load_dword v67, v[34:35], off
	s_cmp_eq_u32 s27, 0
	s_cbranch_scc1 .Lcv_ns_27
	v_lshl_add_u64 v[36:37], v[30:31], 2, v[6:7]
	global_load_dword v99, v[36:37], off
.Lcv_ns_27:
	s_or_b64 exec, exec, s[4:5]
	v_add_u32_e32 v30, 56, v32
	v_cmp_gt_i32_e32 vcc, 0, v30
	v_cmp_le_i32_e64 s[4:5], s6, v30
	v_mov_b32_e32 v68, 0
	v_mov_b32_e32 v100, 0
	s_or_b64 s[4:5], vcc, s[4:5]
	s_nor_b64 s[14:15], s[4:5], s[0:1]
	s_and_saveexec_b64 s[4:5], s[14:15]
	v_mad_u64_u32 v[34:35], vcc, v30, s28, 0
	v_lshl_add_u64 v[34:35], v[34:35], 2, v[8:9]
	global_load_dword v68, v[34:35], off
	s_cmp_eq_u32 s27, 0
	s_cbranch_scc1 .Lcv_ns_28
	v_lshl_add_u64 v[36:37], v[30:31], 2, v[6:7]
	global_load_dword v100, v[36:37], off
; __device__ __forceinline__ void conv_item(const ConvJob& J, const float* W, const float* sc, bf16_t* out, LAS float* scr, int item, int lane) {
;     ...
;   for (int i = 0; i < 32; ++i) { const int cc = 2 * i + (lane >> 5); const int k = c0 + cc - J.k_off; const int n = n0 + (lane & 31);
;     float v = 0.f;
;     if (k >= 0 && k < J.K && n < J.N) { v = W[(size_t)k * J.N + n]; if (J.sc_mode == 1) v *= sc[k]; else if (J.sc_mode == 2) v *= (1.f - sc[k]); }
;     scr[cc * 33 + (lane & 31)] = v; }
.Lcv_ns_28:
	s_or_b64 exec, exec, s[4:5]
	v_add_u32_e32 v30, 58, v32
	v_cmp_gt_i32_e32 vcc, 0, v30
	v_cmp_le_i32_e64 s[4:5], s6, v30
	v_mov_b32_e32 v69, 0
	v_mov_b32_e32 v101, 0
	s_or_b64 s[4:5], vcc, s[4:5]
	s_nor_b64 s[14:15], s[4:5], s[0:1]
	s_and_saveexec_b64 s[4:5], s[14:15]
	v_mad_u64_u32 v[34:35], vcc, v30, s28, 0
	v_lshl_add_u64 v[34:35], v[34:35], 2, v[8:9]
	global_load_dword v69, v[34:35], off
	s_cmp_eq_u32 s27, 0
	s_cbranch_scc1 .Lcv_ns_29
	v_lshl_add_u64 v[36:37], v[30:31], 2, v[6:7]
	global_load_dword v101, v[36:37], off
.Lcv_ns_29:
	s_or_b64 exec, exec, s[4:5]
	v_add_u32_e32 v30, 60, v32
	v_cmp_gt_i32_e32 vcc, 0, v30
	v_cmp_le_i32_e64 s[4:5], s6, v30
	v_mov_b32_e32 v70, 0
	v_mov_b32_e32 v102, 0
	s_or_b64 s[4:5], vcc, s[4:5]
	s_nor_b64 s[14:15], s[4:5], s[0:1]
	s_and_saveexec_b64 s[4:5], s[14:15]
	v_mad_u64_u32 v[34:35], vcc, v30, s28, 0
	v_lshl_add_u64 v[34:35], v[34:35], 2, v[8:9]
	global_load_dword v70, v[34:35], off
	s_cmp_eq_u32 s27, 0
	s_cbranch_scc1 .Lcv_ns_30
	v_lshl_add_u64 v[36:37], v[30:31], 2, v[6:7]
	global_load_dword v102, v[36:37], off
.Lcv_ns_30:
	s_or_b64 exec, exec, s[4:5]
	v_add_u32_e32 v30, 62, v32
	v_cmp_gt_i32_e32 vcc, 0, v30
	v_cmp_le_i32_e64 s[4:5], s6, v30
	v_mov_b32_e32 v71, 0
	v_mov_b32_e32 v103, 0
	s_or_b64 s[4:5], vcc, s[4:5]
	s_nor_b64 s[14:15], s[4:5], s[0:1]
	s_and_saveexec_b64 s[4:5], s[14:15]
	v_mad_u64_u32 v[34:35], vcc, v30, s28, 0
	v_lshl_add_u64 v[34:35], v[34:35], 2, v[8:9]
	global_load_dword v71, v[34:35], off
	s_cmp_eq_u32 s27, 0
	s_cbranch_scc1 .Lcv_ns_31
	v_lshl_add_u64 v[36:37], v[30:31], 2, v[6:7]
	global_load_dword v103, v[36:37], off
.Lcv_ns_31:
	s_or_b64 exec, exec, s[4:5]
	s_waitcnt vmcnt(0)
	s_cmp_eq_u32 s27, 0
	s_cbranch_scc1 .Lcv_wr
	s_cmp_eq_u32 s27, 1
	s_cbranch_scc1 .Lcv_mul
	v_sub_f32_e32 v72, 1.0, v72
	v_sub_f32_e32 v73, 1.0, v73
	v_sub_f32_e32 v74, 1.0, v74
	v_sub_f32_e32 v75, 1.0, v75
	v_sub_f32_e32 v76, 1.0, v76
	v_sub_f32_e32 v77, 1.0, v77
	v_sub_f32_e32 v78, 1.0, v78
	v_sub_f32_e32 v79, 1.0, v79
	v_sub_f32_e32 v80, 1.0, v80
	v_sub_f32_e32 v81, 1.0, v81
	v_sub_f32_e32 v82, 1.0, v82
	v_sub_f32_e32 v83, 1.0, v83
	v_sub_f32_e32 v84, 1.0, v84
	v_sub_f32_e32 v85, 1.0, v85
	v_sub_f32_e32 v86, 1.0, v86
	v_sub_f32_e32 v87, 1.0, v87
	v_sub_f32_e32 v88, 1.0, v88
	v_sub_f32_e32 v89, 1.0, v89
	v_sub_f32_e32 v90, 1.0, v90
	v_sub_f32_e32 v91, 1.0, v91
	v_sub_f32_e32 v92, 1.0, v92
	v_sub_f32_e32 v93, 1.0, v93
	v_sub_f32_e32 v94, 1.0, v94
	v_sub_f32_e32 v95, 1.0, v95
	v_sub_f32_e32 v96, 1.0, v96
	v_sub_f32_e32 v97, 1.0, v97
	v_sub_f32_e32 v98, 1.0, v98
	v_sub_f32_e32 v99, 1.0, v99
	v_sub_f32_e32 v100, 1.0, v100
	v_sub_f32_e32 v101, 1.0, v101
	v_sub_f32_e32 v102, 1.0, v102
	v_sub_f32_e32 v103, 1.0, v103
.Lcv_mul:
	v_mul_f32_e32 v40, v40, v72
	v_mul_f32_e32 v41, v41, v73
	v_mul_f32_e32 v42, v42, v74
	v_mul_f32_e32 v43, v43, v75
	v_mul_f32_e32 v44, v44, v76
	v_mul_f32_e32 v45, v45, v77
	v_mul_f32_e32 v46, v46, v78
	v_mul_f32_e32 v47, v47, v79
	v_mul_f32_e32 v48, v48, v80
	v_mul_f32_e32 v49, v49, v81
	v_mul_f32_e32 v50, v50, v82
	v_mul_f32_e32 v51, v51, v83
	v_mul_f32_e32 v52, v52, v84
	v_mul_f32_e32 v53, v53, v85
	v_mul_f32_e32 v54, v54, v86
	v_mul_f32_e32 v55, v55, v87
	v_mul_f32_e32 v56, v56, v88
	v_mul_f32_e32 v57, v57, v89
	v_mul_f32_e32 v58, v58, v90
	v_mul_f32_e32 v59, v59, v91
	v_mul_f32_e32 v60, v60, v92
	v_mul_f32_e32 v61, v61, v93
	v_mul_f32_e32 v62, v62, v94
	v_mul_f32_e32 v63, v63, v95
	v_mul_f32_e32 v64, v64, v96
	v_mul_f32_e32 v65, v65, v97
	v_mul_f32_e32 v66, v66, v98
	v_mul_f32_e32 v67, v67, v99
	v_mul_f32_e32 v68, v68, v100
	v_mul_f32_e32 v69, v69, v101
	v_mul_f32_e32 v70, v70, v102
	v_mul_f32_e32 v71, v71, v103
.Lcv_wr:
	ds_write_b32 v12, v40
	ds_write_b32 v12, v41 offset:264
	ds_write_b32 v12, v42 offset:528
	ds_write_b32 v12, v43 offset:792
	ds_write_b32 v12, v44 offset:1056
	ds_write_b32 v12, v45 offset:1320
	ds_write_b32 v12, v46 offset:1584
	ds_write_b32 v12, v47 offset:1848
	ds_write_b32 v12, v48 offset:2112
	ds_write_b32 v12, v49 offset:2376
	ds_write_b32 v12, v50 offset:2640
	ds_write_b32 v12, v51 offset:2904
	ds_write_b32 v12, v52 offset:3168
	ds_write_b32 v12, v53 offset:3432
	ds_write_b32 v12, v54 offset:3696
	ds_write_b32 v12, v55 offset:3960
	ds_write_b32 v12, v56 offset:4224
	ds_write_b32 v12, v57 offset:4488
	ds_write_b32 v12, v58 offset:4752
	ds_write_b32 v12, v59 offset:5016
	ds_write_b32 v12, v60 offset:5280
	ds_write_b32 v12, v61 offset:5544
	ds_write_b32 v12, v62 offset:5808
	ds_write_b32 v12, v63 offset:6072
	ds_write_b32 v12, v64 offset:6336
	ds_write_b32 v12, v65 offset:6600
	ds_write_b32 v12, v66 offset:6864
	ds_write_b32 v12, v67 offset:7128
	ds_write_b32 v12, v68 offset:7392
	ds_write_b32 v12, v69 offset:7656
	ds_write_b32 v12, v70 offset:7920
	ds_write_b32 v12, v71 offset:8184
	v_add_u32_e32 v12, 0x2100, v12
	s_add_i32 s36, s36, 64
	s_cmp_eq_u32 s36, 64
	s_cbranch_scc0 .LBB0_926
